# gate/up k-loop: LDS-DMA issue split 5+5 across the barrier step and the next step
# speedup vs baseline: 1.0702x; 1.0051x over previous
.LBB0_83:
	s_ashr_i32 s14, s18, 31
	v_mov_b32_e32 v129, v127
	s_lshr_b32 s14, s14, 27
	s_add_i32 s14, s18, s14
	s_waitcnt vmcnt(6)
	v_ashrrev_i32_e32 v20, 6, v129
	s_waitcnt vmcnt(5)
	v_bfe_u32 v24, v129, 3, 3
	v_lshlrev_b32_e32 v25, 3, v20
	s_ashr_i32 s20, s14, 5
	s_and_b32 s14, s14, 0x3ffffe0
	v_or_b32_e32 v12, v25, v24
	s_sub_i32 s19, s18, s14
	v_lshrrev_b32_e32 v26, 1, v12
	s_mulk_i32 s19, 0xc0
	v_lshrrev_b32_e32 v0, 31, v129
	v_xor_b32_e32 v2, v26, v129
	v_add_u32_e32 v21, v20, v0
	v_and_b32_e32 v23, 63, v129
	v_add_u32_e32 v0, s19, v12
	v_lshlrev_b32_e32 v2, 4, v2
	v_add_u32_e32 v14, 32, v12
	v_ashrrev_i32_e32 v1, 31, v0
	v_and_b32_e32 v124, 0x70, v2
	v_add_u32_e32 v2, s19, v14
	v_add_u32_e32 v16, 64, v12
	s_add_i32 s15, s19, 0x80
	v_lshlrev_b32_e32 v23, 4, v23
	v_lshlrev_b64 v[0:1], 11, v[0:1]
	v_ashrrev_i32_e32 v3, 31, v2
	v_add_u32_e32 v4, s19, v16
	v_add_u32_e32 v18, 0x60, v12
	v_add_u32_e32 v8, s15, v12
	s_add_i32 s15, s19, 0xa0
	v_lshl_or_b32 v142, v20, 10, v23
	v_lshl_add_u64 v[0:1], s[6:7], 0, v[0:1]
	v_lshlrev_b64 v[2:3], 11, v[2:3]
	v_ashrrev_i32_e32 v5, 31, v4
	v_add_u32_e32 v6, s19, v18
	v_add_u32_e32 v10, s15, v12
	v_readfirstlane_b32 s15, v142
	v_add_u32_e32 v144, 0x1000, v142
	v_lshl_add_u64 v[0:1], v[0:1], 0, v[124:125]
	v_lshl_add_u64 v[2:3], s[6:7], 0, v[2:3]
	v_lshlrev_b64 v[4:5], 11, v[4:5]
	v_ashrrev_i32_e32 v7, 31, v6
	s_mov_b32 m0, s15
	v_readfirstlane_b32 s15, v144
	v_add_u32_e32 v145, 0x2000, v142
	s_lshl_b32 s14, s20, 7
	v_lshl_add_u64 v[2:3], v[2:3], 0, v[124:125]
	v_lshl_add_u64 v[4:5], s[6:7], 0, v[4:5]
	v_lshlrev_b64 v[6:7], 11, v[6:7]
	v_ashrrev_i32_e32 v9, 31, v8
	global_load_lds_dwordx4 v[0:1], off
	s_mov_b32 m0, s15
	v_readfirstlane_b32 s15, v145
	v_add_u32_e32 v146, 0x3000, v142
	v_lshl_add_u64 v[4:5], v[4:5], 0, v[124:125]
	v_lshl_add_u64 v[6:7], s[6:7], 0, v[6:7]
	v_lshlrev_b64 v[8:9], 11, v[8:9]
	v_ashrrev_i32_e32 v11, 31, v10
	v_add_u32_e32 v12, s14, v12
	global_load_lds_dwordx4 v[2:3], off
	s_mov_b32 m0, s15
	v_readfirstlane_b32 s15, v146
	v_add_u32_e32 v147, 0x4000, v142
	v_lshl_add_u64 v[6:7], v[6:7], 0, v[124:125]
	v_lshl_add_u64 v[8:9], s[6:7], 0, v[8:9]
	v_lshlrev_b64 v[10:11], 11, v[10:11]
	v_ashrrev_i32_e32 v13, 31, v12
	v_add_u32_e32 v14, s14, v14
	global_load_lds_dwordx4 v[4:5], off
	s_mov_b32 m0, s15
	v_readfirstlane_b32 s15, v147
	v_add_u32_e32 v148, 0x5000, v142
	v_lshl_add_u64 v[8:9], v[8:9], 0, v[124:125]
	v_lshl_add_u64 v[10:11], s[6:7], 0, v[10:11]
	v_lshlrev_b64 v[12:13], 11, v[12:13]
	v_ashrrev_i32_e32 v15, 31, v14
	v_add_u32_e32 v16, s14, v16
	v_add_u32_e32 v143, 0xc000, v142
	global_load_lds_dwordx4 v[6:7], off
	s_mov_b32 m0, s15
	v_readfirstlane_b32 s15, v148
	v_lshl_add_u64 v[10:11], v[10:11], 0, v[124:125]
	v_lshl_add_u64 v[12:13], s[12:13], 0, v[12:13]
	v_lshlrev_b64 v[14:15], 11, v[14:15]
	v_ashrrev_i32_e32 v17, 31, v16
	v_add_u32_e32 v18, s14, v18
	global_load_lds_dwordx4 v[8:9], off
	s_mov_b32 m0, s15
	v_readfirstlane_b32 s15, v143
	v_add_u32_e32 v150, 0xd000, v142
	v_lshl_add_u64 v[12:13], v[12:13], 0, v[124:125]
	v_lshl_add_u64 v[14:15], s[12:13], 0, v[14:15]
	v_lshlrev_b64 v[16:17], 11, v[16:17]
	v_ashrrev_i32_e32 v19, 31, v18
	global_load_lds_dwordx4 v[10:11], off
	s_mov_b32 m0, s15
	v_readfirstlane_b32 s15, v150
	v_add_u32_e32 v153, 0xe000, v142
	v_lshl_add_u64 v[14:15], v[14:15], 0, v[124:125]
	v_lshl_add_u64 v[16:17], s[12:13], 0, v[16:17]
	v_lshlrev_b64 v[18:19], 11, v[18:19]
	global_load_lds_dwordx4 v[12:13], off
	s_mov_b32 m0, s15
	v_readfirstlane_b32 s15, v153
	v_add_u32_e32 v154, 0xf000, v142
	v_lshl_add_u64 v[16:17], v[16:17], 0, v[124:125]
	v_lshl_add_u64 v[18:19], s[12:13], 0, v[18:19]
	global_load_lds_dwordx4 v[14:15], off
	s_mov_b32 m0, s15
	v_readfirstlane_b32 s15, v154
	v_lshl_add_u64 v[18:19], v[18:19], 0, v[124:125]
	global_load_lds_dwordx4 v[16:17], off
	s_mov_b32 m0, s15
	v_lshrrev_b32_e32 v22, 1, v21
	global_load_lds_dwordx4 v[18:19], off
	v_and_b32_e32 v149, 31, v129
	v_mul_lo_u32 v152, v22, s80
	v_and_b32_e32 v0, -2, v21
	v_or_b32_e32 v1, v152, v149
	v_sub_u32_e32 v151, v20, v0
	v_lshlrev_b32_e32 v155, 7, v1
	v_lshlrev_b32_e32 v1, 7, v149
	v_lshrrev_b32_e32 v23, 1, v129
	v_lshl_or_b32 v182, v151, 13, v1
	v_bfe_u32 v1, v129, 5, 1
	v_bfe_u32 v0, v129, 1, 3
	v_bitop3_b32 v2, v1, v23, 7 bitop3:0x78
	v_lshlrev_b32_e32 v184, 4, v2
	v_bitop3_b32 v2, v1, v0, 2 bitop3:0x36
	v_lshlrev_b32_e32 v185, 4, v2
	v_bitop3_b32 v2, v1, v0, 4 bitop3:0x36
	v_bitop3_b32 v0, v1, v0, 6 bitop3:0x36
	v_lshlrev_b32_e32 v187, 4, v0
	v_bitop3_b32 v0, v26, 7, v129 bitop3:0x48
	s_mul_i32 s15, s18, 0xc0
	v_lshlrev_b32_e32 v124, 4, v0
	v_or_b32_e32 v0, s15, v24
	v_add_u32_e32 v0, v0, v25
	s_mul_i32 s21, s20, 0x1800
	v_subrev_u32_e32 v0, s21, v0
	v_ashrrev_i32_e32 v1, 31, v0
	v_or_b32_e32 v4, 32, v24
	v_lshlrev_b32_e32 v186, 4, v2
	v_lshlrev_b64 v[2:3], 11, v[0:1]
	v_or_b32_e32 v1, s15, v4
	v_add_u32_e32 v1, v1, v25
	v_lshl_add_u64 v[96:97], s[6:7], 0, v[2:3]
	v_subrev_u32_e32 v2, s21, v1
	v_ashrrev_i32_e32 v3, 31, v2
	v_or_b32_e32 v5, 64, v24
	v_lshlrev_b64 v[2:3], 11, v[2:3]
	v_add3_u32 v1, v5, s15, v25
	v_lshl_add_u64 v[98:99], s[6:7], 0, v[2:3]
	v_subrev_u32_e32 v2, s21, v1
	v_ashrrev_i32_e32 v3, 31, v2
	v_or_b32_e32 v6, 0x60, v24
	v_lshlrev_b64 v[2:3], 11, v[2:3]
	v_add3_u32 v1, v6, s15, v25
	v_lshl_add_u64 v[100:101], s[6:7], 0, v[2:3]
	v_subrev_u32_e32 v2, s21, v1
	v_ashrrev_i32_e32 v3, 31, v2
	v_lshlrev_b64 v[2:3], 11, v[2:3]
	v_lshl_add_u64 v[102:103], s[6:7], 0, v[2:3]
	v_add_u32_e32 v2, 0x80, v0
	v_add_u32_e32 v0, 0xa0, v0
	v_ashrrev_i32_e32 v1, 31, v0
	v_lshlrev_b64 v[0:1], 11, v[0:1]
	v_lshl_add_u64 v[106:107], s[6:7], 0, v[0:1]
	v_or_b32_e32 v0, s14, v24
	v_add_u32_e32 v0, v0, v25
	v_ashrrev_i32_e32 v1, 31, v0
	v_lshlrev_b64 v[0:1], 11, v[0:1]
	v_lshl_add_u64 v[108:109], s[10:11], 0, v[0:1]
	v_or_b32_e32 v0, s14, v4
	v_add_u32_e32 v0, v0, v25
	v_ashrrev_i32_e32 v1, 31, v0
	v_lshlrev_b64 v[0:1], 11, v[0:1]
	v_lshl_add_u64 v[110:111], s[10:11], 0, v[0:1]
	v_or_b32_e32 v0, s14, v5
	v_add_u32_e32 v0, v0, v25
	v_ashrrev_i32_e32 v1, 31, v0
	v_lshlrev_b64 v[0:1], 11, v[0:1]
	v_lshl_add_u64 v[112:113], s[10:11], 0, v[0:1]
	v_or_b32_e32 v0, s14, v6
	v_add_u32_e32 v0, v0, v25
	s_waitcnt vmcnt(0)
	v_ashrrev_i32_e32 v3, 31, v2
	v_ashrrev_i32_e32 v1, 31, v0
	v_lshlrev_b64 v[2:3], 11, v[2:3]
	v_lshlrev_b64 v[0:1], 11, v[0:1]
	v_mov_b32_e32 v64, 0
	v_add_u32_e32 v183, 0x10000, v182
	v_lshl_add_u64 v[104:105], s[6:7], 0, v[2:3]
	v_lshl_add_u64 v[114:115], s[10:11], 0, v[0:1]
	s_mov_b32 s21, 0
	v_mov_b32_e32 v65, v64
	v_mov_b32_e32 v66, v64
	v_mov_b32_e32 v67, v64
	v_mov_b32_e32 v68, v64
	v_mov_b32_e32 v69, v64
	v_mov_b32_e32 v70, v64
	v_mov_b32_e32 v71, v64
	v_mov_b32_e32 v72, v64
	v_mov_b32_e32 v73, v64
	v_mov_b32_e32 v74, v64
	v_mov_b32_e32 v75, v64
	v_mov_b32_e32 v76, v64
	v_mov_b32_e32 v77, v64
	v_mov_b32_e32 v78, v64
	v_mov_b32_e32 v79, v64
	v_mov_b32_e32 v80, v64
	v_mov_b32_e32 v81, v64
	v_mov_b32_e32 v82, v64
	v_mov_b32_e32 v83, v64
	v_mov_b32_e32 v84, v64
	v_mov_b32_e32 v85, v64
	v_mov_b32_e32 v86, v64
	v_mov_b32_e32 v87, v64
	v_mov_b32_e32 v88, v64
	v_mov_b32_e32 v89, v64
	v_mov_b32_e32 v90, v64
	v_mov_b32_e32 v91, v64
	v_mov_b32_e32 v92, v64
	v_mov_b32_e32 v93, v64
	v_mov_b32_e32 v94, v64
	v_mov_b32_e32 v95, v64
	v_mov_b32_e32 v32, v64
	v_mov_b32_e32 v33, v64
	v_mov_b32_e32 v34, v64
	v_mov_b32_e32 v35, v64
	v_mov_b32_e32 v36, v64
	v_mov_b32_e32 v37, v64
	v_mov_b32_e32 v38, v64
	v_mov_b32_e32 v39, v64
	v_mov_b32_e32 v40, v64
	v_mov_b32_e32 v41, v64
	v_mov_b32_e32 v42, v64
	v_mov_b32_e32 v43, v64
	v_mov_b32_e32 v44, v64
	v_mov_b32_e32 v45, v64
	v_mov_b32_e32 v46, v64
	v_mov_b32_e32 v47, v64
	v_mov_b32_e32 v48, v64
	v_mov_b32_e32 v49, v64
	v_mov_b32_e32 v50, v64
	v_mov_b32_e32 v51, v64
	v_mov_b32_e32 v52, v64
	v_mov_b32_e32 v53, v64
	v_mov_b32_e32 v54, v64
	v_mov_b32_e32 v55, v64
	v_mov_b32_e32 v56, v64
	v_mov_b32_e32 v57, v64
	v_mov_b32_e32 v58, v64
	v_mov_b32_e32 v59, v64
	v_mov_b32_e32 v60, v64
	v_mov_b32_e32 v61, v64
	v_mov_b32_e32 v62, v64
	v_mov_b32_e32 v63, v64
	v_mov_b32_e32 v0, v64
	v_mov_b32_e32 v1, v64
	v_mov_b32_e32 v2, v64
	v_mov_b32_e32 v3, v64
	v_mov_b32_e32 v4, v64
	v_mov_b32_e32 v5, v64
	v_mov_b32_e32 v6, v64
	v_mov_b32_e32 v7, v64
	v_mov_b32_e32 v8, v64
	v_mov_b32_e32 v9, v64
	v_mov_b32_e32 v10, v64
	v_mov_b32_e32 v11, v64
	v_mov_b32_e32 v12, v64
	v_mov_b32_e32 v13, v64
	v_mov_b32_e32 v14, v64
	v_mov_b32_e32 v15, v64
	v_mov_b32_e32 v16, v64
	v_mov_b32_e32 v17, v64
	v_mov_b32_e32 v18, v64
	v_mov_b32_e32 v19, v64
	v_mov_b32_e32 v20, v64
	v_mov_b32_e32 v21, v64
	v_mov_b32_e32 v22, v64
	v_mov_b32_e32 v23, v64
	v_mov_b32_e32 v24, v64
	v_mov_b32_e32 v25, v64
	v_mov_b32_e32 v26, v64
	v_mov_b32_e32 v27, v64
	s_waitcnt vmcnt(0)
	v_mov_b32_e32 v28, v64
	v_mov_b32_e32 v29, v64
	v_mov_b32_e32 v30, v64
	v_mov_b32_e32 v31, v64
	s_waitcnt vmcnt(0) lgkmcnt(0)
	s_barrier
	v_readfirstlane_b32 s101, v142
	s_sub_u32 vcc_lo, s12, s10
	s_subb_u32 vcc_hi, s13, s11
	v_mov_b32_e32 v130, v124
	v_mov_b32_e32 v131, 0
	v_lshl_add_u64 v[108:109], v[108:109], 0, vcc
	v_lshl_add_u64 v[110:111], v[110:111], 0, vcc
	v_lshl_add_u64 v[112:113], v[112:113], 0, vcc
	v_lshl_add_u64 v[114:115], v[114:115], 0, vcc
	v_lshl_add_u64 v[96:97], v[96:97], 0, v[130:131]
	v_lshl_add_u64 v[98:99], v[98:99], 0, v[130:131]
	v_lshl_add_u64 v[100:101], v[100:101], 0, v[130:131]
	v_lshl_add_u64 v[102:103], v[102:103], 0, v[130:131]
	v_lshl_add_u64 v[104:105], v[104:105], 0, v[130:131]
	v_lshl_add_u64 v[106:107], v[106:107], 0, v[130:131]
	v_lshl_add_u64 v[108:109], v[108:109], 0, v[130:131]
	v_lshl_add_u64 v[110:111], v[110:111], 0, v[130:131]
	v_lshl_add_u64 v[112:113], v[112:113], 0, v[130:131]
	v_lshl_add_u64 v[114:115], v[114:115], 0, v[130:131]
	v_add_u32_e32 v116, v155, v184
	v_add_u32_e32 v117, v155, v185
	v_add_u32_e32 v118, v155, v186
	v_add_u32_e32 v119, v155, v187
	v_add_u32_e32 v120, v182, v184
	v_add_u32_e32 v121, v182, v185
	v_add_u32_e32 v122, v182, v186
	v_add_u32_e32 v123, v182, v187
	v_add_u32_e32 v120, 0x8000, v120
	v_add_u32_e32 v121, 0x8000, v121
	v_add_u32_e32 v122, 0x8000, v122
	v_add_u32_e32 v123, 0x8000, v123
	v_lshl_add_u64 v[96:97], v[96:97], 0, s[2:3]
	v_lshl_add_u64 v[98:99], v[98:99], 0, s[2:3]
	v_lshl_add_u64 v[100:101], v[100:101], 0, s[2:3]
	v_lshl_add_u64 v[102:103], v[102:103], 0, s[2:3]
	v_lshl_add_u64 v[104:105], v[104:105], 0, s[2:3]
	v_lshl_add_u64 v[106:107], v[106:107], 0, s[2:3]
	v_lshl_add_u64 v[108:109], v[108:109], 0, s[2:3]
	v_lshl_add_u64 v[110:111], v[110:111], 0, s[2:3]
	v_lshl_add_u64 v[112:113], v[112:113], 0, s[2:3]
	v_lshl_add_u64 v[114:115], v[114:115], 0, s[2:3]
	ds_read_b128 v[192:195], v116 offset:0
	ds_read_b128 v[204:207], v120 offset:16384
	ds_read_b128 v[208:211], v120 offset:20480
	ds_read_b128 v[196:199], v116 offset:4096
	ds_read_b128 v[200:203], v116 offset:8192
	s_add_u32 m0, s101, 0x6000
	s_nop 0
	global_load_lds_dwordx4 v[96:97], off
	v_lshl_add_u64 v[96:97], v[96:97], 0, s[2:3]
	s_add_u32 m0, s101, 0x7000
	s_nop 0
	global_load_lds_dwordx4 v[98:99], off
	v_lshl_add_u64 v[98:99], v[98:99], 0, s[2:3]
	s_add_u32 m0, s101, 0x8000
	s_nop 0
	global_load_lds_dwordx4 v[100:101], off
	v_lshl_add_u64 v[100:101], v[100:101], 0, s[2:3]
	s_add_u32 m0, s101, 0x9000
	s_nop 0
	global_load_lds_dwordx4 v[102:103], off
	v_lshl_add_u64 v[102:103], v[102:103], 0, s[2:3]
	s_add_u32 m0, s101, 0xa000
	s_nop 0
	global_load_lds_dwordx4 v[104:105], off
	v_lshl_add_u64 v[104:105], v[104:105], 0, s[2:3]
	s_mov_b32 s100, 7
.Lgu2_loop:
	s_waitcnt lgkmcnt(3)
	v_mfma_f32_32x32x16_bf16 v[64:79], v[192:195], v[204:207], v[64:79]
	s_add_u32 m0, s101, 0xb000
	ds_read_b128 v[212:215], v117 offset:0
	global_load_lds_dwordx4 v[106:107], off
	v_lshl_add_u64 v[106:107], v[106:107], 0, s[2:3]
	s_waitcnt lgkmcnt(3)
	v_mfma_f32_32x32x16_bf16 v[80:95], v[192:195], v[208:211], v[80:95]
	s_add_u32 m0, s101, 0x10000
	ds_read_b128 v[224:227], v121 offset:16384
	global_load_lds_dwordx4 v[108:109], off
	v_lshl_add_u64 v[108:109], v[108:109], 0, s[2:3]
	s_waitcnt lgkmcnt(3)
	v_mfma_f32_32x32x16_bf16 v[32:47], v[196:199], v[204:207], v[32:47]
	s_add_u32 m0, s101, 0x11000
	ds_read_b128 v[228:231], v121 offset:20480
	global_load_lds_dwordx4 v[110:111], off
	v_lshl_add_u64 v[110:111], v[110:111], 0, s[2:3]
	v_mfma_f32_32x32x16_bf16 v[48:63], v[196:199], v[208:211], v[48:63]
	s_add_u32 m0, s101, 0x12000
	ds_read_b128 v[216:219], v117 offset:4096
	global_load_lds_dwordx4 v[112:113], off
	v_lshl_add_u64 v[112:113], v[112:113], 0, s[2:3]
	s_waitcnt lgkmcnt(4)
	v_mfma_f32_32x32x16_bf16 v[0:15], v[200:203], v[204:207], v[0:15]
	s_add_u32 m0, s101, 0x13000
	ds_read_b128 v[220:223], v117 offset:8192
	global_load_lds_dwordx4 v[114:115], off
	v_lshl_add_u64 v[114:115], v[114:115], 0, s[2:3]
	v_mfma_f32_32x32x16_bf16 v[16:31], v[200:203], v[208:211], v[16:31]
	s_waitcnt lgkmcnt(3)
	v_mfma_f32_32x32x16_bf16 v[64:79], v[212:215], v[224:227], v[64:79]
	ds_read_b128 v[192:195], v118 offset:0
	s_waitcnt lgkmcnt(3)
	v_mfma_f32_32x32x16_bf16 v[80:95], v[212:215], v[228:231], v[80:95]
	ds_read_b128 v[204:207], v122 offset:16384
	s_waitcnt lgkmcnt(3)
	v_mfma_f32_32x32x16_bf16 v[32:47], v[216:219], v[224:227], v[32:47]
	ds_read_b128 v[208:211], v122 offset:20480
	v_mfma_f32_32x32x16_bf16 v[48:63], v[216:219], v[228:231], v[48:63]
	ds_read_b128 v[196:199], v118 offset:4096
	s_waitcnt lgkmcnt(4)
	v_mfma_f32_32x32x16_bf16 v[0:15], v[220:223], v[224:227], v[0:15]
	ds_read_b128 v[200:203], v118 offset:8192
	v_mfma_f32_32x32x16_bf16 v[16:31], v[220:223], v[228:231], v[16:31]
	s_waitcnt lgkmcnt(3)
	v_mfma_f32_32x32x16_bf16 v[64:79], v[192:195], v[204:207], v[64:79]
	ds_read_b128 v[212:215], v119 offset:0
	s_waitcnt lgkmcnt(3)
	v_mfma_f32_32x32x16_bf16 v[80:95], v[192:195], v[208:211], v[80:95]
	ds_read_b128 v[224:227], v123 offset:16384
	s_waitcnt lgkmcnt(3)
	v_mfma_f32_32x32x16_bf16 v[32:47], v[196:199], v[204:207], v[32:47]
	ds_read_b128 v[228:231], v123 offset:20480
	v_mfma_f32_32x32x16_bf16 v[48:63], v[196:199], v[208:211], v[48:63]
	ds_read_b128 v[216:219], v119 offset:4096
	s_waitcnt lgkmcnt(4)
	v_mfma_f32_32x32x16_bf16 v[0:15], v[200:203], v[204:207], v[0:15]
	ds_read_b128 v[220:223], v119 offset:8192
	v_mfma_f32_32x32x16_bf16 v[16:31], v[200:203], v[208:211], v[16:31]
	s_waitcnt vmcnt(0) lgkmcnt(0)
	s_barrier
	v_mfma_f32_32x32x16_bf16 v[64:79], v[212:215], v[224:227], v[64:79]
	s_add_u32 m0, s101, 0x0
	ds_read_b128 v[192:195], v116 offset:24576
	global_load_lds_dwordx4 v[96:97], off
	v_lshl_add_u64 v[96:97], v[96:97], 0, s[2:3]
	v_mfma_f32_32x32x16_bf16 v[80:95], v[212:215], v[228:231], v[80:95]
	s_add_u32 m0, s101, 0x1000
	ds_read_b128 v[204:207], v120 offset:32768
	global_load_lds_dwordx4 v[98:99], off
	v_lshl_add_u64 v[98:99], v[98:99], 0, s[2:3]
	v_mfma_f32_32x32x16_bf16 v[32:47], v[216:219], v[224:227], v[32:47]
	s_add_u32 m0, s101, 0x2000
	ds_read_b128 v[208:211], v120 offset:36864
	global_load_lds_dwordx4 v[100:101], off
	v_lshl_add_u64 v[100:101], v[100:101], 0, s[2:3]
	v_mfma_f32_32x32x16_bf16 v[48:63], v[216:219], v[228:231], v[48:63]
	s_add_u32 m0, s101, 0x3000
	ds_read_b128 v[196:199], v116 offset:28672
	global_load_lds_dwordx4 v[102:103], off
	v_lshl_add_u64 v[102:103], v[102:103], 0, s[2:3]
	v_mfma_f32_32x32x16_bf16 v[0:15], v[220:223], v[224:227], v[0:15]
	s_add_u32 m0, s101, 0x4000
	ds_read_b128 v[200:203], v116 offset:32768
	global_load_lds_dwordx4 v[104:105], off
	v_lshl_add_u64 v[104:105], v[104:105], 0, s[2:3]
	v_mfma_f32_32x32x16_bf16 v[16:31], v[220:223], v[228:231], v[16:31]
	s_waitcnt lgkmcnt(3)
	v_mfma_f32_32x32x16_bf16 v[64:79], v[192:195], v[204:207], v[64:79]
	s_add_u32 m0, s101, 0x5000
	ds_read_b128 v[212:215], v117 offset:24576
	global_load_lds_dwordx4 v[106:107], off
	v_lshl_add_u64 v[106:107], v[106:107], 0, s[2:3]
	s_waitcnt lgkmcnt(3)
	v_mfma_f32_32x32x16_bf16 v[80:95], v[192:195], v[208:211], v[80:95]
	s_add_u32 m0, s101, 0xc000
	ds_read_b128 v[224:227], v121 offset:32768
	global_load_lds_dwordx4 v[108:109], off
	v_lshl_add_u64 v[108:109], v[108:109], 0, s[2:3]
	s_waitcnt lgkmcnt(3)
	v_mfma_f32_32x32x16_bf16 v[32:47], v[196:199], v[204:207], v[32:47]
	s_add_u32 m0, s101, 0xd000
	ds_read_b128 v[228:231], v121 offset:36864
	global_load_lds_dwordx4 v[110:111], off
	v_lshl_add_u64 v[110:111], v[110:111], 0, s[2:3]
	v_mfma_f32_32x32x16_bf16 v[48:63], v[196:199], v[208:211], v[48:63]
	s_add_u32 m0, s101, 0xe000
	ds_read_b128 v[216:219], v117 offset:28672
	global_load_lds_dwordx4 v[112:113], off
	v_lshl_add_u64 v[112:113], v[112:113], 0, s[2:3]
	s_waitcnt lgkmcnt(4)
	v_mfma_f32_32x32x16_bf16 v[0:15], v[200:203], v[204:207], v[0:15]
	s_add_u32 m0, s101, 0xf000
	ds_read_b128 v[220:223], v117 offset:32768
	global_load_lds_dwordx4 v[114:115], off
	v_lshl_add_u64 v[114:115], v[114:115], 0, s[2:3]
	v_mfma_f32_32x32x16_bf16 v[16:31], v[200:203], v[208:211], v[16:31]
	s_waitcnt lgkmcnt(3)
	v_mfma_f32_32x32x16_bf16 v[64:79], v[212:215], v[224:227], v[64:79]
	ds_read_b128 v[192:195], v118 offset:24576
	s_waitcnt lgkmcnt(3)
	v_mfma_f32_32x32x16_bf16 v[80:95], v[212:215], v[228:231], v[80:95]
	ds_read_b128 v[204:207], v122 offset:32768
	s_waitcnt lgkmcnt(3)
	v_mfma_f32_32x32x16_bf16 v[32:47], v[216:219], v[224:227], v[32:47]
	ds_read_b128 v[208:211], v122 offset:36864
	v_mfma_f32_32x32x16_bf16 v[48:63], v[216:219], v[228:231], v[48:63]
	ds_read_b128 v[196:199], v118 offset:28672
	s_waitcnt lgkmcnt(4)
	v_mfma_f32_32x32x16_bf16 v[0:15], v[220:223], v[224:227], v[0:15]
	ds_read_b128 v[200:203], v118 offset:32768
	v_mfma_f32_32x32x16_bf16 v[16:31], v[220:223], v[228:231], v[16:31]
	s_waitcnt lgkmcnt(3)
	v_mfma_f32_32x32x16_bf16 v[64:79], v[192:195], v[204:207], v[64:79]
	ds_read_b128 v[212:215], v119 offset:24576
	s_waitcnt lgkmcnt(3)
	v_mfma_f32_32x32x16_bf16 v[80:95], v[192:195], v[208:211], v[80:95]
	ds_read_b128 v[224:227], v123 offset:32768
	s_waitcnt lgkmcnt(3)
	v_mfma_f32_32x32x16_bf16 v[32:47], v[196:199], v[204:207], v[32:47]
	ds_read_b128 v[228:231], v123 offset:36864
	v_mfma_f32_32x32x16_bf16 v[48:63], v[196:199], v[208:211], v[48:63]
	ds_read_b128 v[216:219], v119 offset:28672
	s_waitcnt lgkmcnt(4)
	v_mfma_f32_32x32x16_bf16 v[0:15], v[200:203], v[204:207], v[0:15]
	ds_read_b128 v[220:223], v119 offset:32768
	v_mfma_f32_32x32x16_bf16 v[16:31], v[200:203], v[208:211], v[16:31]
	s_waitcnt vmcnt(0) lgkmcnt(0)
	s_barrier
	v_mfma_f32_32x32x16_bf16 v[64:79], v[212:215], v[224:227], v[64:79]
	s_add_u32 m0, s101, 0x6000
	ds_read_b128 v[192:195], v116 offset:0
	global_load_lds_dwordx4 v[96:97], off
	v_lshl_add_u64 v[96:97], v[96:97], 0, s[2:3]
	v_mfma_f32_32x32x16_bf16 v[80:95], v[212:215], v[228:231], v[80:95]
	s_add_u32 m0, s101, 0x7000
	ds_read_b128 v[204:207], v120 offset:16384
	global_load_lds_dwordx4 v[98:99], off
	v_lshl_add_u64 v[98:99], v[98:99], 0, s[2:3]
	v_mfma_f32_32x32x16_bf16 v[32:47], v[216:219], v[224:227], v[32:47]
	s_add_u32 m0, s101, 0x8000
	ds_read_b128 v[208:211], v120 offset:20480
	global_load_lds_dwordx4 v[100:101], off
	v_lshl_add_u64 v[100:101], v[100:101], 0, s[2:3]
	v_mfma_f32_32x32x16_bf16 v[48:63], v[216:219], v[228:231], v[48:63]
	s_add_u32 m0, s101, 0x9000
	ds_read_b128 v[196:199], v116 offset:4096
	global_load_lds_dwordx4 v[102:103], off
	v_lshl_add_u64 v[102:103], v[102:103], 0, s[2:3]
	v_mfma_f32_32x32x16_bf16 v[0:15], v[220:223], v[224:227], v[0:15]
	s_add_u32 m0, s101, 0xa000
	ds_read_b128 v[200:203], v116 offset:8192
	global_load_lds_dwordx4 v[104:105], off
	v_lshl_add_u64 v[104:105], v[104:105], 0, s[2:3]
	v_mfma_f32_32x32x16_bf16 v[16:31], v[220:223], v[228:231], v[16:31]
	s_add_i32 s100, s100, -1
	s_cmp_lg_u32 s100, 0
	s_cbranch_scc1 .Lgu2_loop
	s_waitcnt lgkmcnt(3)
	v_mfma_f32_32x32x16_bf16 v[64:79], v[192:195], v[204:207], v[64:79]
	s_add_u32 m0, s101, 0xb000
	ds_read_b128 v[212:215], v117 offset:0
	global_load_lds_dwordx4 v[106:107], off
	v_lshl_add_u64 v[106:107], v[106:107], 0, s[2:3]
	s_waitcnt lgkmcnt(3)
	v_mfma_f32_32x32x16_bf16 v[80:95], v[192:195], v[208:211], v[80:95]
	s_add_u32 m0, s101, 0x10000
	ds_read_b128 v[224:227], v121 offset:16384
	global_load_lds_dwordx4 v[108:109], off
	v_lshl_add_u64 v[108:109], v[108:109], 0, s[2:3]
	s_waitcnt lgkmcnt(3)
	v_mfma_f32_32x32x16_bf16 v[32:47], v[196:199], v[204:207], v[32:47]
	s_add_u32 m0, s101, 0x11000
	ds_read_b128 v[228:231], v121 offset:20480
	global_load_lds_dwordx4 v[110:111], off
	v_lshl_add_u64 v[110:111], v[110:111], 0, s[2:3]
	v_mfma_f32_32x32x16_bf16 v[48:63], v[196:199], v[208:211], v[48:63]
	s_add_u32 m0, s101, 0x12000
	ds_read_b128 v[216:219], v117 offset:4096
	global_load_lds_dwordx4 v[112:113], off
	v_lshl_add_u64 v[112:113], v[112:113], 0, s[2:3]
	s_waitcnt lgkmcnt(4)
	v_mfma_f32_32x32x16_bf16 v[0:15], v[200:203], v[204:207], v[0:15]
	s_add_u32 m0, s101, 0x13000
	ds_read_b128 v[220:223], v117 offset:8192
	global_load_lds_dwordx4 v[114:115], off
	v_lshl_add_u64 v[114:115], v[114:115], 0, s[2:3]
	v_mfma_f32_32x32x16_bf16 v[16:31], v[200:203], v[208:211], v[16:31]
	s_waitcnt lgkmcnt(3)
	v_mfma_f32_32x32x16_bf16 v[64:79], v[212:215], v[224:227], v[64:79]
	ds_read_b128 v[192:195], v118 offset:0
	s_waitcnt lgkmcnt(3)
	v_mfma_f32_32x32x16_bf16 v[80:95], v[212:215], v[228:231], v[80:95]
	ds_read_b128 v[204:207], v122 offset:16384
	s_waitcnt lgkmcnt(3)
	v_mfma_f32_32x32x16_bf16 v[32:47], v[216:219], v[224:227], v[32:47]
	ds_read_b128 v[208:211], v122 offset:20480
	v_mfma_f32_32x32x16_bf16 v[48:63], v[216:219], v[228:231], v[48:63]
	ds_read_b128 v[196:199], v118 offset:4096
	s_waitcnt lgkmcnt(4)
	v_mfma_f32_32x32x16_bf16 v[0:15], v[220:223], v[224:227], v[0:15]
	ds_read_b128 v[200:203], v118 offset:8192
	v_mfma_f32_32x32x16_bf16 v[16:31], v[220:223], v[228:231], v[16:31]
	s_waitcnt lgkmcnt(3)
	v_mfma_f32_32x32x16_bf16 v[64:79], v[192:195], v[204:207], v[64:79]
	ds_read_b128 v[212:215], v119 offset:0
	s_waitcnt lgkmcnt(3)
	v_mfma_f32_32x32x16_bf16 v[80:95], v[192:195], v[208:211], v[80:95]
	ds_read_b128 v[224:227], v123 offset:16384
	s_waitcnt lgkmcnt(3)
	v_mfma_f32_32x32x16_bf16 v[32:47], v[196:199], v[204:207], v[32:47]
	ds_read_b128 v[228:231], v123 offset:20480
	v_mfma_f32_32x32x16_bf16 v[48:63], v[196:199], v[208:211], v[48:63]
	ds_read_b128 v[216:219], v119 offset:4096
	s_waitcnt lgkmcnt(4)
	v_mfma_f32_32x32x16_bf16 v[0:15], v[200:203], v[204:207], v[0:15]
	ds_read_b128 v[220:223], v119 offset:8192
	v_mfma_f32_32x32x16_bf16 v[16:31], v[200:203], v[208:211], v[16:31]
	s_waitcnt vmcnt(0) lgkmcnt(0)
	s_barrier
	v_mfma_f32_32x32x16_bf16 v[64:79], v[212:215], v[224:227], v[64:79]
	ds_read_b128 v[192:195], v116 offset:24576
	v_mfma_f32_32x32x16_bf16 v[80:95], v[212:215], v[228:231], v[80:95]
	ds_read_b128 v[204:207], v120 offset:32768
	v_mfma_f32_32x32x16_bf16 v[32:47], v[216:219], v[224:227], v[32:47]
	ds_read_b128 v[208:211], v120 offset:36864
	v_mfma_f32_32x32x16_bf16 v[48:63], v[216:219], v[228:231], v[48:63]
	ds_read_b128 v[196:199], v116 offset:28672
	v_mfma_f32_32x32x16_bf16 v[0:15], v[220:223], v[224:227], v[0:15]
	ds_read_b128 v[200:203], v116 offset:32768
	v_mfma_f32_32x32x16_bf16 v[16:31], v[220:223], v[228:231], v[16:31]
	s_waitcnt lgkmcnt(3)
	v_mfma_f32_32x32x16_bf16 v[64:79], v[192:195], v[204:207], v[64:79]
	ds_read_b128 v[212:215], v117 offset:24576
	s_waitcnt lgkmcnt(3)
	v_mfma_f32_32x32x16_bf16 v[80:95], v[192:195], v[208:211], v[80:95]
	ds_read_b128 v[224:227], v121 offset:32768
	s_waitcnt lgkmcnt(3)
	v_mfma_f32_32x32x16_bf16 v[32:47], v[196:199], v[204:207], v[32:47]
	ds_read_b128 v[228:231], v121 offset:36864
	v_mfma_f32_32x32x16_bf16 v[48:63], v[196:199], v[208:211], v[48:63]
	ds_read_b128 v[216:219], v117 offset:28672
	s_waitcnt lgkmcnt(4)
	v_mfma_f32_32x32x16_bf16 v[0:15], v[200:203], v[204:207], v[0:15]
	ds_read_b128 v[220:223], v117 offset:32768
	v_mfma_f32_32x32x16_bf16 v[16:31], v[200:203], v[208:211], v[16:31]
	s_waitcnt lgkmcnt(3)
	v_mfma_f32_32x32x16_bf16 v[64:79], v[212:215], v[224:227], v[64:79]
	ds_read_b128 v[192:195], v118 offset:24576
	s_waitcnt lgkmcnt(3)
	v_mfma_f32_32x32x16_bf16 v[80:95], v[212:215], v[228:231], v[80:95]
	ds_read_b128 v[204:207], v122 offset:32768
	s_waitcnt lgkmcnt(3)
	v_mfma_f32_32x32x16_bf16 v[32:47], v[216:219], v[224:227], v[32:47]
	ds_read_b128 v[208:211], v122 offset:36864
	v_mfma_f32_32x32x16_bf16 v[48:63], v[216:219], v[228:231], v[48:63]
	ds_read_b128 v[196:199], v118 offset:28672
	s_waitcnt lgkmcnt(4)
	v_mfma_f32_32x32x16_bf16 v[0:15], v[220:223], v[224:227], v[0:15]
	ds_read_b128 v[200:203], v118 offset:32768
	v_mfma_f32_32x32x16_bf16 v[16:31], v[220:223], v[228:231], v[16:31]
	s_waitcnt lgkmcnt(3)
	v_mfma_f32_32x32x16_bf16 v[64:79], v[192:195], v[204:207], v[64:79]
	ds_read_b128 v[212:215], v119 offset:24576
	s_waitcnt lgkmcnt(3)
	v_mfma_f32_32x32x16_bf16 v[80:95], v[192:195], v[208:211], v[80:95]
	ds_read_b128 v[224:227], v123 offset:32768
	s_waitcnt lgkmcnt(3)
	v_mfma_f32_32x32x16_bf16 v[32:47], v[196:199], v[204:207], v[32:47]
	ds_read_b128 v[228:231], v123 offset:36864
	v_mfma_f32_32x32x16_bf16 v[48:63], v[196:199], v[208:211], v[48:63]
	ds_read_b128 v[216:219], v119 offset:28672
	s_waitcnt lgkmcnt(4)
	v_mfma_f32_32x32x16_bf16 v[0:15], v[200:203], v[204:207], v[0:15]
	ds_read_b128 v[220:223], v119 offset:32768
	v_mfma_f32_32x32x16_bf16 v[16:31], v[200:203], v[208:211], v[16:31]
	s_waitcnt vmcnt(0) lgkmcnt(0)
	s_barrier
	v_mfma_f32_32x32x16_bf16 v[64:79], v[212:215], v[224:227], v[64:79]
	v_mfma_f32_32x32x16_bf16 v[80:95], v[212:215], v[228:231], v[80:95]
	v_mfma_f32_32x32x16_bf16 v[32:47], v[216:219], v[224:227], v[32:47]
	v_mfma_f32_32x32x16_bf16 v[48:63], v[216:219], v[228:231], v[48:63]
	v_mfma_f32_32x32x16_bf16 v[0:15], v[220:223], v[224:227], v[0:15]
	v_mfma_f32_32x32x16_bf16 v[16:31], v[220:223], v[228:231], v[16:31]
	s_nop 7
	s_nop 7
	s_branch .LBB0_82

.LBB0_1336:
	s_ashr_i32 s14, s16, 31
	v_mov_b32_e32 v129, v127
	s_lshr_b32 s14, s14, 27
	s_add_i32 s14, s16, s14
	v_ashrrev_i32_e32 v20, 6, v129
	v_bfe_u32 v24, v129, 3, 3
	v_lshlrev_b32_e32 v25, 3, v20
	s_ashr_i32 s18, s14, 5
	s_and_b32 s14, s14, 0x3ffffe0
	v_or_b32_e32 v12, v25, v24
	s_sub_i32 s17, s16, s14
	v_lshrrev_b32_e32 v26, 1, v12
	s_mulk_i32 s17, 0xc0
	v_lshrrev_b32_e32 v0, 31, v129
	v_xor_b32_e32 v2, v26, v129
	v_add_u32_e32 v21, v20, v0
	v_and_b32_e32 v23, 63, v129
	v_add_u32_e32 v0, s17, v12
	v_lshlrev_b32_e32 v2, 4, v2
	v_add_u32_e32 v14, 32, v12
	v_ashrrev_i32_e32 v1, 31, v0
	v_and_b32_e32 v124, 0x70, v2
	v_add_u32_e32 v2, s17, v14
	v_add_u32_e32 v16, 64, v12
	s_add_i32 s15, s17, 0x80
	v_lshlrev_b32_e32 v23, 4, v23
	v_lshlrev_b64 v[0:1], 11, v[0:1]
	v_ashrrev_i32_e32 v3, 31, v2
	v_add_u32_e32 v4, s17, v16
	v_add_u32_e32 v18, 0x60, v12
	v_add_u32_e32 v8, s15, v12
	s_add_i32 s15, s17, 0xa0
	v_lshl_or_b32 v142, v20, 10, v23
	v_lshl_add_u64 v[0:1], s[6:7], 0, v[0:1]
	v_lshlrev_b64 v[2:3], 11, v[2:3]
	v_ashrrev_i32_e32 v5, 31, v4
	v_add_u32_e32 v6, s17, v18
	v_add_u32_e32 v10, s15, v12
	v_readfirstlane_b32 s15, v142
	v_add_u32_e32 v144, 0x1000, v142
	v_lshl_add_u64 v[0:1], v[0:1], 0, v[124:125]
	v_lshl_add_u64 v[2:3], s[6:7], 0, v[2:3]
	v_lshlrev_b64 v[4:5], 11, v[4:5]
	v_ashrrev_i32_e32 v7, 31, v6
	s_mov_b32 m0, s15
	v_readfirstlane_b32 s15, v144
	v_add_u32_e32 v145, 0x2000, v142
	s_lshl_b32 s14, s18, 7
	v_lshl_add_u64 v[2:3], v[2:3], 0, v[124:125]
	v_lshl_add_u64 v[4:5], s[6:7], 0, v[4:5]
	v_lshlrev_b64 v[6:7], 11, v[6:7]
	v_ashrrev_i32_e32 v9, 31, v8
	global_load_lds_dwordx4 v[0:1], off
	s_mov_b32 m0, s15
	v_readfirstlane_b32 s15, v145
	v_add_u32_e32 v146, 0x3000, v142
	v_lshl_add_u64 v[4:5], v[4:5], 0, v[124:125]
	v_lshl_add_u64 v[6:7], s[6:7], 0, v[6:7]
	v_lshlrev_b64 v[8:9], 11, v[8:9]
	v_ashrrev_i32_e32 v11, 31, v10
	v_add_u32_e32 v12, s14, v12
	global_load_lds_dwordx4 v[2:3], off
	s_mov_b32 m0, s15
	v_readfirstlane_b32 s15, v146
	v_add_u32_e32 v147, 0x4000, v142
	v_lshl_add_u64 v[6:7], v[6:7], 0, v[124:125]
	v_lshl_add_u64 v[8:9], s[6:7], 0, v[8:9]
	v_lshlrev_b64 v[10:11], 11, v[10:11]
	v_ashrrev_i32_e32 v13, 31, v12
	v_add_u32_e32 v14, s14, v14
	global_load_lds_dwordx4 v[4:5], off
	s_mov_b32 m0, s15
	v_readfirstlane_b32 s15, v147
	v_add_u32_e32 v148, 0x5000, v142
	v_lshl_add_u64 v[8:9], v[8:9], 0, v[124:125]
	v_lshl_add_u64 v[10:11], s[6:7], 0, v[10:11]
	v_lshlrev_b64 v[12:13], 11, v[12:13]
	v_ashrrev_i32_e32 v15, 31, v14
	v_add_u32_e32 v16, s14, v16
	v_add_u32_e32 v143, 0xc000, v142
	global_load_lds_dwordx4 v[6:7], off
	s_mov_b32 m0, s15
	v_readfirstlane_b32 s15, v148
	v_lshl_add_u64 v[10:11], v[10:11], 0, v[124:125]
	v_lshl_add_u64 v[12:13], s[10:11], 0, v[12:13]
	v_lshlrev_b64 v[14:15], 11, v[14:15]
	v_ashrrev_i32_e32 v17, 31, v16
	v_add_u32_e32 v18, s14, v18
	global_load_lds_dwordx4 v[8:9], off
	s_mov_b32 m0, s15
	v_readfirstlane_b32 s15, v143
	v_add_u32_e32 v150, 0xd000, v142
	v_lshl_add_u64 v[12:13], v[12:13], 0, v[124:125]
	v_lshl_add_u64 v[14:15], s[10:11], 0, v[14:15]
	v_lshlrev_b64 v[16:17], 11, v[16:17]
	v_ashrrev_i32_e32 v19, 31, v18
	global_load_lds_dwordx4 v[10:11], off
	s_mov_b32 m0, s15
	v_readfirstlane_b32 s15, v150
	v_add_u32_e32 v153, 0xe000, v142
	v_lshl_add_u64 v[14:15], v[14:15], 0, v[124:125]
	v_lshl_add_u64 v[16:17], s[10:11], 0, v[16:17]
	v_lshlrev_b64 v[18:19], 11, v[18:19]
	global_load_lds_dwordx4 v[12:13], off
	s_mov_b32 m0, s15
	v_readfirstlane_b32 s15, v153
	v_add_u32_e32 v154, 0xf000, v142
	v_lshl_add_u64 v[16:17], v[16:17], 0, v[124:125]
	v_lshl_add_u64 v[18:19], s[10:11], 0, v[18:19]
	global_load_lds_dwordx4 v[14:15], off
	s_mov_b32 m0, s15
	v_readfirstlane_b32 s15, v154
	v_lshl_add_u64 v[18:19], v[18:19], 0, v[124:125]
	global_load_lds_dwordx4 v[16:17], off
	s_mov_b32 m0, s15
	v_lshrrev_b32_e32 v22, 1, v21
	global_load_lds_dwordx4 v[18:19], off
	v_and_b32_e32 v149, 31, v129
	v_mul_lo_u32 v152, v22, s80
	v_and_b32_e32 v0, -2, v21
	v_or_b32_e32 v1, v152, v149
	v_sub_u32_e32 v151, v20, v0
	v_lshlrev_b32_e32 v155, 7, v1
	v_lshlrev_b32_e32 v1, 7, v149
	v_lshrrev_b32_e32 v23, 1, v129
	v_lshl_or_b32 v182, v151, 13, v1
	v_bfe_u32 v1, v129, 5, 1
	v_bfe_u32 v0, v129, 1, 3
	v_bitop3_b32 v2, v1, v23, 7 bitop3:0x78
	v_lshlrev_b32_e32 v184, 4, v2
	v_bitop3_b32 v2, v1, v0, 2 bitop3:0x36
	v_lshlrev_b32_e32 v185, 4, v2
	v_bitop3_b32 v2, v1, v0, 4 bitop3:0x36
	v_bitop3_b32 v0, v1, v0, 6 bitop3:0x36
	v_lshlrev_b32_e32 v187, 4, v0
	v_bitop3_b32 v0, v26, 7, v129 bitop3:0x48
	s_mul_i32 s15, s16, 0xc0
	v_lshlrev_b32_e32 v124, 4, v0
	v_or_b32_e32 v0, s15, v24
	v_add_u32_e32 v0, v0, v25
	s_mul_i32 s19, s18, 0x1800
	v_subrev_u32_e32 v0, s19, v0
	v_ashrrev_i32_e32 v1, 31, v0
	v_or_b32_e32 v4, 32, v24
	v_lshlrev_b32_e32 v186, 4, v2
	v_lshlrev_b64 v[2:3], 11, v[0:1]
	v_or_b32_e32 v1, s15, v4
	v_add_u32_e32 v1, v1, v25
	v_lshl_add_u64 v[96:97], s[6:7], 0, v[2:3]
	v_subrev_u32_e32 v2, s19, v1
	v_ashrrev_i32_e32 v3, 31, v2
	v_or_b32_e32 v5, 64, v24
	v_lshlrev_b64 v[2:3], 11, v[2:3]
	v_add3_u32 v1, v5, s15, v25
	v_lshl_add_u64 v[98:99], s[6:7], 0, v[2:3]
	v_subrev_u32_e32 v2, s19, v1
	v_ashrrev_i32_e32 v3, 31, v2
	v_or_b32_e32 v6, 0x60, v24
	v_lshlrev_b64 v[2:3], 11, v[2:3]
	v_add3_u32 v1, v6, s15, v25
	v_lshl_add_u64 v[100:101], s[6:7], 0, v[2:3]
	v_subrev_u32_e32 v2, s19, v1
	v_ashrrev_i32_e32 v3, 31, v2
	v_lshlrev_b64 v[2:3], 11, v[2:3]
	v_lshl_add_u64 v[102:103], s[6:7], 0, v[2:3]
	v_add_u32_e32 v2, 0x80, v0
	v_add_u32_e32 v0, 0xa0, v0
	v_ashrrev_i32_e32 v1, 31, v0
	v_lshlrev_b64 v[0:1], 11, v[0:1]
	v_lshl_add_u64 v[106:107], s[6:7], 0, v[0:1]
	v_or_b32_e32 v0, s14, v24
	v_add_u32_e32 v0, v0, v25
	v_ashrrev_i32_e32 v1, 31, v0
	v_lshlrev_b64 v[0:1], 11, v[0:1]
	v_lshl_add_u64 v[108:109], s[12:13], 0, v[0:1]
	v_or_b32_e32 v0, s14, v4
	v_add_u32_e32 v0, v0, v25
	v_ashrrev_i32_e32 v1, 31, v0
	v_lshlrev_b64 v[0:1], 11, v[0:1]
	v_lshl_add_u64 v[110:111], s[12:13], 0, v[0:1]
	v_or_b32_e32 v0, s14, v5
	v_add_u32_e32 v0, v0, v25
	v_ashrrev_i32_e32 v1, 31, v0
	v_lshlrev_b64 v[0:1], 11, v[0:1]
	v_lshl_add_u64 v[112:113], s[12:13], 0, v[0:1]
	v_or_b32_e32 v0, s14, v6
	v_add_u32_e32 v0, v0, v25
	s_waitcnt vmcnt(0)
	v_ashrrev_i32_e32 v3, 31, v2
	v_ashrrev_i32_e32 v1, 31, v0
	v_lshlrev_b64 v[2:3], 11, v[2:3]
	v_lshlrev_b64 v[0:1], 11, v[0:1]
	v_mov_b32_e32 v64, 0
	v_add_u32_e32 v183, 0x10000, v182
	v_lshl_add_u64 v[104:105], s[6:7], 0, v[2:3]
	v_lshl_add_u64 v[114:115], s[12:13], 0, v[0:1]
	s_mov_b32 s19, 0
	v_mov_b32_e32 v65, v64
	v_mov_b32_e32 v66, v64
	v_mov_b32_e32 v67, v64
	v_mov_b32_e32 v68, v64
	v_mov_b32_e32 v69, v64
	v_mov_b32_e32 v70, v64
	v_mov_b32_e32 v71, v64
	v_mov_b32_e32 v72, v64
	v_mov_b32_e32 v73, v64
	v_mov_b32_e32 v74, v64
	v_mov_b32_e32 v75, v64
	v_mov_b32_e32 v76, v64
	v_mov_b32_e32 v77, v64
	v_mov_b32_e32 v78, v64
	v_mov_b32_e32 v79, v64
	v_mov_b32_e32 v80, v64
	v_mov_b32_e32 v81, v64
	v_mov_b32_e32 v82, v64
	v_mov_b32_e32 v83, v64
	v_mov_b32_e32 v84, v64
	v_mov_b32_e32 v85, v64
	v_mov_b32_e32 v86, v64
	v_mov_b32_e32 v87, v64
	v_mov_b32_e32 v88, v64
	v_mov_b32_e32 v89, v64
	v_mov_b32_e32 v90, v64
	v_mov_b32_e32 v91, v64
	v_mov_b32_e32 v92, v64
	v_mov_b32_e32 v93, v64
	v_mov_b32_e32 v94, v64
	v_mov_b32_e32 v95, v64
	v_mov_b32_e32 v32, v64
	v_mov_b32_e32 v33, v64
	v_mov_b32_e32 v34, v64
	v_mov_b32_e32 v35, v64
	v_mov_b32_e32 v36, v64
	v_mov_b32_e32 v37, v64
	v_mov_b32_e32 v38, v64
	v_mov_b32_e32 v39, v64
	v_mov_b32_e32 v40, v64
	v_mov_b32_e32 v41, v64
	v_mov_b32_e32 v42, v64
	v_mov_b32_e32 v43, v64
	v_mov_b32_e32 v44, v64
	v_mov_b32_e32 v45, v64
	v_mov_b32_e32 v46, v64
	v_mov_b32_e32 v47, v64
	v_mov_b32_e32 v48, v64
	v_mov_b32_e32 v49, v64
	v_mov_b32_e32 v50, v64
	v_mov_b32_e32 v51, v64
	v_mov_b32_e32 v52, v64
	v_mov_b32_e32 v53, v64
	v_mov_b32_e32 v54, v64
	v_mov_b32_e32 v55, v64
	v_mov_b32_e32 v56, v64
	v_mov_b32_e32 v57, v64
	v_mov_b32_e32 v58, v64
	v_mov_b32_e32 v59, v64
	v_mov_b32_e32 v60, v64
	v_mov_b32_e32 v61, v64
	v_mov_b32_e32 v62, v64
	v_mov_b32_e32 v63, v64
	v_mov_b32_e32 v0, v64
	v_mov_b32_e32 v1, v64
	v_mov_b32_e32 v2, v64
	v_mov_b32_e32 v3, v64
	v_mov_b32_e32 v4, v64
	v_mov_b32_e32 v5, v64
	v_mov_b32_e32 v6, v64
	v_mov_b32_e32 v7, v64
	v_mov_b32_e32 v8, v64
	v_mov_b32_e32 v9, v64
	v_mov_b32_e32 v10, v64
	v_mov_b32_e32 v11, v64
	v_mov_b32_e32 v12, v64
	v_mov_b32_e32 v13, v64
	v_mov_b32_e32 v14, v64
	v_mov_b32_e32 v15, v64
	v_mov_b32_e32 v16, v64
	v_mov_b32_e32 v17, v64
	v_mov_b32_e32 v18, v64
	v_mov_b32_e32 v19, v64
	v_mov_b32_e32 v20, v64
	v_mov_b32_e32 v21, v64
	v_mov_b32_e32 v22, v64
	v_mov_b32_e32 v23, v64
	v_mov_b32_e32 v24, v64
	v_mov_b32_e32 v25, v64
	v_mov_b32_e32 v26, v64
	v_mov_b32_e32 v27, v64
	v_mov_b32_e32 v28, v64
	v_mov_b32_e32 v29, v64
	v_mov_b32_e32 v30, v64
	v_mov_b32_e32 v31, v64
	s_waitcnt vmcnt(0) lgkmcnt(0)
	s_barrier
	v_readfirstlane_b32 s101, v142
	s_sub_u32 vcc_lo, s10, s12
	s_subb_u32 vcc_hi, s11, s13
	v_mov_b32_e32 v130, v124
	v_mov_b32_e32 v131, 0
	v_lshl_add_u64 v[108:109], v[108:109], 0, vcc
	v_lshl_add_u64 v[110:111], v[110:111], 0, vcc
	v_lshl_add_u64 v[112:113], v[112:113], 0, vcc
	v_lshl_add_u64 v[114:115], v[114:115], 0, vcc
	v_lshl_add_u64 v[96:97], v[96:97], 0, v[130:131]
	v_lshl_add_u64 v[98:99], v[98:99], 0, v[130:131]
	v_lshl_add_u64 v[100:101], v[100:101], 0, v[130:131]
	v_lshl_add_u64 v[102:103], v[102:103], 0, v[130:131]
	v_lshl_add_u64 v[104:105], v[104:105], 0, v[130:131]
	v_lshl_add_u64 v[106:107], v[106:107], 0, v[130:131]
	v_lshl_add_u64 v[108:109], v[108:109], 0, v[130:131]
	v_lshl_add_u64 v[110:111], v[110:111], 0, v[130:131]
	v_lshl_add_u64 v[112:113], v[112:113], 0, v[130:131]
	v_lshl_add_u64 v[114:115], v[114:115], 0, v[130:131]
	v_add_u32_e32 v116, v155, v184
	v_add_u32_e32 v117, v155, v185
	v_add_u32_e32 v118, v155, v186
	v_add_u32_e32 v119, v155, v187
	v_add_u32_e32 v120, v182, v184
	v_add_u32_e32 v121, v182, v185
	v_add_u32_e32 v122, v182, v186
	v_add_u32_e32 v123, v182, v187
	v_add_u32_e32 v120, 0x8000, v120
	v_add_u32_e32 v121, 0x8000, v121
	v_add_u32_e32 v122, 0x8000, v122
	v_add_u32_e32 v123, 0x8000, v123
	v_lshl_add_u64 v[96:97], v[96:97], 0, s[2:3]
	v_lshl_add_u64 v[98:99], v[98:99], 0, s[2:3]
	v_lshl_add_u64 v[100:101], v[100:101], 0, s[2:3]
	v_lshl_add_u64 v[102:103], v[102:103], 0, s[2:3]
	v_lshl_add_u64 v[104:105], v[104:105], 0, s[2:3]
	v_lshl_add_u64 v[106:107], v[106:107], 0, s[2:3]
	v_lshl_add_u64 v[108:109], v[108:109], 0, s[2:3]
	v_lshl_add_u64 v[110:111], v[110:111], 0, s[2:3]
	v_lshl_add_u64 v[112:113], v[112:113], 0, s[2:3]
	v_lshl_add_u64 v[114:115], v[114:115], 0, s[2:3]
	ds_read_b128 v[192:195], v116 offset:0
	ds_read_b128 v[204:207], v120 offset:16384
	ds_read_b128 v[208:211], v120 offset:20480
	ds_read_b128 v[196:199], v116 offset:4096
	ds_read_b128 v[200:203], v116 offset:8192
	s_add_u32 m0, s101, 0x6000
	s_nop 0
	global_load_lds_dwordx4 v[96:97], off
	v_lshl_add_u64 v[96:97], v[96:97], 0, s[2:3]
	s_add_u32 m0, s101, 0x7000
	s_nop 0
	global_load_lds_dwordx4 v[98:99], off
	v_lshl_add_u64 v[98:99], v[98:99], 0, s[2:3]
	s_add_u32 m0, s101, 0x8000
	s_nop 0
	global_load_lds_dwordx4 v[100:101], off
	v_lshl_add_u64 v[100:101], v[100:101], 0, s[2:3]
	s_add_u32 m0, s101, 0x9000
	s_nop 0
	global_load_lds_dwordx4 v[102:103], off
	v_lshl_add_u64 v[102:103], v[102:103], 0, s[2:3]
	s_add_u32 m0, s101, 0xa000
	s_nop 0
	global_load_lds_dwordx4 v[104:105], off
	v_lshl_add_u64 v[104:105], v[104:105], 0, s[2:3]
	s_mov_b32 s100, 7
